# out GEMM: same pair-issued LDS-DMA + 128-byte-row LDS image as the proj GEMM
# speedup vs baseline: 1.1563x; 1.0101x over previous
.LBB0_1423:
	s_or_b64 exec, exec, s[6:7]
	s_cmpk_gt_i32 s38, 0x3ff
	s_barrier
	s_cbranch_scc1 .LBB0_1456
	v_lshrrev_b32_e32 v1, 4, v253
	v_bitop3_b32 v1, v1, v166, 3 bitop3:0x78
	v_lshrrev_b32_e32 v0, 2, v253
	v_lshlrev_b32_e32 v137, 3, v1
	v_lshrrev_b32_e32 v1, 1, v166
	v_lshlrev_b32_e32 v2, 6, v166
	v_lshl_or_b32 v136, v167, 5, v0
	v_lshrrev_b32_e32 v0, 5, v253
	v_and_b32_e32 v138, 0x1c0, v1
	v_lshlrev_b32_e32 v1, 6, v253
	v_and_b32_e32 v2, 0x3c0, v2
	v_and_b32_e32 v3, 64, v166
	s_movk_i32 s0, 0x400
	v_bfe_u32 v6, v166, 2, 2
	v_lshlrev_b32_e32 v4, 6, v3
	v_and_or_b32 v1, v1, s0, v2
	v_bitop3_b32 v5, v0, v148, 3 bitop3:0x78
	v_bitop3_b32 v0, v0, v6, 2 bitop3:0x36
	s_movk_i32 s0, 0x2000
	v_lshl_or_b32 v2, v138, 6, v1
	v_lshlrev_b32_e32 v5, 4, v5
	v_lshlrev_b32_e32 v0, 4, v0
	v_or3_b32 v1, v4, v1, s0
	v_lshlrev_b32_e32 v128, 2, v3
	v_mov_b32_e32 v129, 0
	v_or_b32_e32 v139, v2, v5
	v_or_b32_e32 v140, v2, v0
	v_or_b32_e32 v141, v1, v5
	v_or_b32_e32 v142, v1, v0
	v_or_b32_e32 v143, 64, v137
	v_or_b32_e32 v144, 0x60, v137
	v_lshl_add_u64 v[130:131], s[40:41], 0, v[128:129]
	v_lshl_add_u64 v[132:133], s[46:47], 0, v[128:129]
	s_lshl_b32 s0, s38, 4
	s_lshl_b32 s1, s37, 4
	s_movk_i32 s2, 0x440
	v_add_u32_e32 v145, 0x400, v149
	v_add_u32_e32 v146, 0x2000, v149
	s_mov_b64 s[6:7], 0x8800
	v_add_u32_e32 v147, 0x2400, v149
	v_add_u32_e32 v148, 0x4000, v149
	v_add_u32_e32 v150, 0x4400, v149
	v_add_u32_e32 v151, 0x6000, v149
	s_mov_b64 s[8:9], 0x8840
	v_add_u32_e32 v152, 0x6400, v149
	v_add_u32_e32 v153, 0x8000, v149
	v_add_u32_e32 v154, 0x8400, v149
	s_mov_b64 s[10:11], 0x80
	v_add_u32_e32 v155, 0xa000, v149
	s_mov_b64 s[12:13], 0x8880
	v_add_u32_e32 v156, 0xa400, v149
	v_add_u32_e32 v157, 0xc000, v149
	v_add_u32_e32 v158, 0xc400, v149
	s_mov_b64 s[14:15], 0xc0
	v_add_u32_e32 v159, 0xe000, v149
	s_mov_b64 s[16:17], 0x88c0
	v_add_u32_e32 v160, 0xe400, v149
	s_mov_b64 s[18:19], 0x100
	s_mov_b64 s[20:21], 0x140
	s_mov_b64 s[22:23], 0x180
	s_mov_b64 s[24:25], 0x1c0
	s_mov_b32 s27, 0
	v_lshrrev_b32_e32 v100, 3, v253
	v_and_b32_e32 v101, 7, v253
	v_bfe_u32 v102, v253, 4, 2
	v_xor_b32_e32 v101, v101, v102
	v_lshlrev_b32_e32 v150, 3, v101
	v_xor_b32_e32 v101, 4, v101
	v_lshlrev_b32_e32 v151, 3, v101
	v_lshrrev_b32_e32 v105, 6, v166
	v_lshl_or_b32 v152, v105, 5, v100
	v_and_b32_e32 v100, 15, v253
	v_bfe_u32 v101, v253, 4, 1
	v_lshl_or_b32 v100, v101, 4, v100
	v_lshrrev_b32_e32 v101, 7, v166
	v_bfe_u32 v102, v166, 6, 1
	v_lshl_or_b32 v101, v101, 6, v100
	v_lshl_or_b32 v102, v102, 6, v100
	v_lshlrev_b32_e32 v101, 7, v101
	v_lshlrev_b32_e32 v102, 7, v102
	v_add_u32_e32 v102, 0x4000, v102
	v_bfe_u32 v103, v253, 1, 3
	v_lshrrev_b32_e32 v104, 5, v253
	v_mov_b32_e32 v105, v104
	v_xor_b32_e32 v105, v105, v103
	v_lshl_add_u32 v139, v105, 4, v101
	v_or_b32_e32 v105, 2, v104
	v_xor_b32_e32 v105, v105, v103
	v_lshl_add_u32 v140, v105, 4, v101
	v_mov_b32_e32 v105, v104
	v_xor_b32_e32 v105, v105, v103
	v_lshl_add_u32 v141, v105, 4, v102
	v_or_b32_e32 v105, 2, v104
	v_xor_b32_e32 v105, v105, v103
	v_lshl_add_u32 v142, v105, 4, v102
	v_or_b32_e32 v105, 4, v104
	v_xor_b32_e32 v105, v105, v103
	v_lshl_add_u32 v157, v105, 4, v101
	v_or_b32_e32 v105, 6, v104
	v_xor_b32_e32 v105, v105, v103
	v_lshl_add_u32 v158, v105, 4, v101
	v_or_b32_e32 v105, 4, v104
	v_xor_b32_e32 v105, v105, v103
	v_lshl_add_u32 v159, v105, 4, v102
	v_or_b32_e32 v105, 6, v104
	v_xor_b32_e32 v105, v105, v103
	v_lshl_add_u32 v160, v105, 4, v102
	s_branch .LBB0_1426

.LBB0_1426:
	s_lshl_b32 s3, s0, 7
	s_and_b32 s26, s3, 0x3800
	s_lshl_b32 s3, s38, 4
	s_and_b32 s5, s3, 0x70
	s_ashr_i32 s28, s38, 6
	s_add_i32 s5, s5, s28
	s_lshl_b32 s5, s5, 7
	s_and_b32 s3, s3, 0x380
	v_add_u32_e32 v0, s5, v152
	v_mul_lo_u32 v8, v0, s2
	v_add_u32_e32 v0, s3, v152
	v_mul_lo_u32 v9, v0, s2
	v_add_u32_e32 v153, v8, v150
	v_add_u32_e32 v154, v8, v151
	v_add_u32_e32 v155, v9, v150
	v_add_u32_e32 v156, v9, v151
	v_mov_b32_e32 v135, v129
	s_waitcnt vmcnt(0)
	v_readfirstlane_b32 s98, v149
	s_nop 0
	s_lshl_b32 s98, s98, 1
	v_add_u32_e32 v128, 0x0, v153
	s_add_u32 m0, s98, 0x0
	v_lshl_add_u64 v[0:1], v[128:129], 1, s[88:89]
	global_load_lds_dwordx4 v[0:1], off
	v_add_u32_e32 v128, 0x2200, v154
	s_add_u32 m0, s98, 0x400
	v_lshl_add_u64 v[0:1], v[128:129], 1, s[88:89]
	global_load_lds_dwordx4 v[0:1], off
	v_add_u32_e32 v128, 0x4400, v153
	s_add_u32 m0, s98, 0x800
	v_lshl_add_u64 v[0:1], v[128:129], 1, s[88:89]
	global_load_lds_dwordx4 v[0:1], off
	v_add_u32_e32 v128, 0x6600, v154
	s_add_u32 m0, s98, 0xc00
	v_lshl_add_u64 v[0:1], v[128:129], 1, s[88:89]
	global_load_lds_dwordx4 v[0:1], off
	v_add_u32_e32 v128, 0x0, v155
	s_add_u32 m0, s98, 0x4000
	v_lshl_add_u64 v[0:1], v[128:129], 1, s[50:51]
	global_load_lds_dwordx4 v[0:1], off
	v_add_u32_e32 v128, 0x2200, v156
	s_add_u32 m0, s98, 0x4400
	v_lshl_add_u64 v[0:1], v[128:129], 1, s[50:51]
	global_load_lds_dwordx4 v[0:1], off
	v_add_u32_e32 v128, 0x4400, v155
	s_add_u32 m0, s98, 0x4800
	v_lshl_add_u64 v[0:1], v[128:129], 1, s[50:51]
	global_load_lds_dwordx4 v[0:1], off
	v_add_u32_e32 v128, 0x6600, v156
	s_add_u32 m0, s98, 0x4c00
	v_lshl_add_u64 v[0:1], v[128:129], 1, s[50:51]
	global_load_lds_dwordx4 v[0:1], off
	v_readfirstlane_b32 s98, v149
	s_nop 0
	s_lshl_b32 s98, s98, 1
	v_add_u32_e32 v128, 0x40, v153
	s_add_u32 m0, s98, 0x8000
	v_lshl_add_u64 v[0:1], v[128:129], 1, s[88:89]
	global_load_lds_dwordx4 v[0:1], off
	v_add_u32_e32 v128, 0x2240, v154
	s_add_u32 m0, s98, 0x8400
	v_lshl_add_u64 v[0:1], v[128:129], 1, s[88:89]
	global_load_lds_dwordx4 v[0:1], off
	v_add_u32_e32 v128, 0x4440, v153
	s_add_u32 m0, s98, 0x8800
	v_lshl_add_u64 v[0:1], v[128:129], 1, s[88:89]
	global_load_lds_dwordx4 v[0:1], off
	v_add_u32_e32 v128, 0x6640, v154
	s_add_u32 m0, s98, 0x8c00
	v_lshl_add_u64 v[0:1], v[128:129], 1, s[88:89]
	global_load_lds_dwordx4 v[0:1], off
	v_add_u32_e32 v128, 0x40, v155
	s_add_u32 m0, s98, 0xc000
	v_lshl_add_u64 v[0:1], v[128:129], 1, s[50:51]
	global_load_lds_dwordx4 v[0:1], off
	v_add_u32_e32 v128, 0x2240, v156
	s_add_u32 m0, s98, 0xc400
	v_lshl_add_u64 v[0:1], v[128:129], 1, s[50:51]
	global_load_lds_dwordx4 v[0:1], off
	v_add_u32_e32 v128, 0x4440, v155
	s_add_u32 m0, s98, 0xc800
	v_lshl_add_u64 v[0:1], v[128:129], 1, s[50:51]
	global_load_lds_dwordx4 v[0:1], off
	v_add_u32_e32 v128, 0x6640, v156
	s_add_u32 m0, s98, 0xcc00
	v_lshl_add_u64 v[0:1], v[128:129], 1, s[50:51]
	global_load_lds_dwordx4 v[0:1], off
	s_waitcnt vmcnt(8)
	s_waitcnt lgkmcnt(0)
	s_barrier
	s_mov_b32 s26, 0
	s_mov_b32 s33, 0
	v_mov_b32_e32 v0, v129
	v_mov_b32_e32 v1, v129
	v_mov_b32_e32 v2, v129
	v_mov_b32_e32 v3, v129
	v_mov_b32_e32 v4, v129
	v_mov_b32_e32 v5, v129
	v_mov_b32_e32 v6, v129
	v_mov_b32_e32 v7, v129
	v_mov_b32_e32 v8, v129
	v_mov_b32_e32 v9, v129
	v_mov_b32_e32 v10, v129
	v_mov_b32_e32 v11, v129
	v_mov_b32_e32 v12, v129
	v_mov_b32_e32 v13, v129
	v_mov_b32_e32 v14, v129
	v_mov_b32_e32 v15, v129
	s_waitcnt vmcnt(0)
	v_mov_b32_e32 v16, v129
	v_mov_b32_e32 v17, v129
	v_mov_b32_e32 v18, v129
	v_mov_b32_e32 v19, v129
	v_mov_b32_e32 v20, v129
	v_mov_b32_e32 v21, v129
	v_mov_b32_e32 v22, v129
	v_mov_b32_e32 v23, v129
	v_mov_b32_e32 v24, v129
	v_mov_b32_e32 v25, v129
	v_mov_b32_e32 v26, v129
	v_mov_b32_e32 v27, v129
	v_mov_b32_e32 v28, v129
	v_mov_b32_e32 v29, v129
	v_mov_b32_e32 v30, v129
	v_mov_b32_e32 v31, v129
	v_mov_b32_e32 v32, v129
	v_mov_b32_e32 v33, v129
	v_mov_b32_e32 v34, v129
	v_mov_b32_e32 v35, v129
	v_mov_b32_e32 v36, v129
	v_mov_b32_e32 v37, v129
	v_mov_b32_e32 v38, v129
	v_mov_b32_e32 v39, v129
	v_mov_b32_e32 v40, v129
	v_mov_b32_e32 v41, v129
	v_mov_b32_e32 v42, v129
	v_mov_b32_e32 v43, v129
	v_mov_b32_e32 v44, v129
	v_mov_b32_e32 v45, v129
	v_mov_b32_e32 v46, v129
	v_mov_b32_e32 v47, v129
	v_mov_b32_e32 v48, v129
	v_mov_b32_e32 v49, v129
	v_mov_b32_e32 v50, v129
	v_mov_b32_e32 v51, v129
	v_mov_b32_e32 v52, v129
	v_mov_b32_e32 v53, v129
	v_mov_b32_e32 v54, v129
	v_mov_b32_e32 v55, v129
	v_mov_b32_e32 v56, v129
	v_mov_b32_e32 v57, v129
	v_mov_b32_e32 v58, v129
	v_mov_b32_e32 v59, v129
	v_mov_b32_e32 v60, v129
	v_mov_b32_e32 v61, v129
	v_mov_b32_e32 v62, v129
	v_mov_b32_e32 v63, v129
	ds_read_b128 v[64:67], v139 offset:0x0
	ds_read_b128 v[68:71], v139 offset:0x1000
	ds_read_b128 v[76:79], v141 offset:0x0
	ds_read_b128 v[80:83], v141 offset:0x1000
	ds_read_b128 v[84:87], v140 offset:0x0
	ds_read_b128 v[72:75], v140 offset:0x1000
	ds_read_b128 v[92:95], v142 offset:0x0
	ds_read_b128 v[88:91], v142 offset:0x1000
	s_branch .LBB0_1429
.LBB0_1427:
	ds_read_b128 v[64:67], v139 offset:0x0
	ds_read_b128 v[68:71], v139 offset:0x1000
	ds_read_b128 v[76:79], v141 offset:0x0
	ds_read_b128 v[80:83], v141 offset:0x1000
	ds_read_b128 v[84:87], v140 offset:0x0
	ds_read_b128 v[72:75], v140 offset:0x1000
	ds_read_b128 v[92:95], v142 offset:0x0
	ds_read_b128 v[88:91], v142 offset:0x1000

.LBB0_1431:
	v_mfma_f32_32x32x16_bf16 v[48:63], v[64:67], v[76:79], v[48:63]
	s_mov_b64 s[30:31], -1
	s_and_b64 vcc, exec, s[28:29]
	v_mfma_f32_32x32x16_bf16 v[32:47], v[64:67], v[80:83], v[32:47]
	v_mfma_f32_32x32x16_bf16 v[16:31], v[68:71], v[76:79], v[16:31]
	ds_read_b128 v[76:79], v157 offset:0x0
	ds_read_b128 v[64:67], v157 offset:0x1000
	v_mfma_f32_32x32x16_bf16 v[0:15], v[68:71], v[80:83], v[0:15]
	v_mfma_f32_32x32x16_bf16 v[48:63], v[84:87], v[92:95], v[48:63]
	v_mfma_f32_32x32x16_bf16 v[32:47], v[84:87], v[88:91], v[32:47]
	ds_read_b128 v[84:87], v159 offset:0x0
	v_mfma_f32_32x32x16_bf16 v[16:31], v[72:75], v[92:95], v[16:31]
	ds_read_b128 v[92:95], v159 offset:0x1000
	ds_read_b128 v[68:71], v158 offset:0x0
	ds_read_b128 v[96:99], v158 offset:0x1000
	ds_read_b128 v[80:83], v160 offset:0x0
	ds_read_b128 v[100:103], v160 offset:0x1000
	v_mfma_f32_32x32x16_bf16 v[0:15], v[72:75], v[88:91], v[0:15]
	s_waitcnt vmcnt(0)
.LBB0_1439:
	s_waitcnt lgkmcnt(0)
	s_cmp_gt_u32 s33, 26
	s_cselect_b64 s[30:31], -1, 0
	s_and_b64 vcc, exec, s[30:31]
	s_barrier
	s_cbranch_vccnz .LBB0_1441
	v_readfirstlane_b32 s98, v149
	s_nop 0
	s_lshl_b32 s98, s98, 1
	s_add_u32 s99, s26, 0x80
	v_add_u32_e32 v128, s99, v153
	s_add_u32 m0, s98, 0x0
	v_lshl_add_u64 v[72:73], v[128:129], 1, s[88:89]
	global_load_lds_dwordx4 v[72:73], off
	s_add_u32 s99, s26, 0x2280
	v_add_u32_e32 v128, s99, v154
	s_add_u32 m0, s98, 0x400
	v_lshl_add_u64 v[72:73], v[128:129], 1, s[88:89]
	global_load_lds_dwordx4 v[72:73], off
	s_add_u32 s99, s26, 0x4480
	v_add_u32_e32 v128, s99, v153
	s_add_u32 m0, s98, 0x800
	v_lshl_add_u64 v[72:73], v[128:129], 1, s[88:89]
	global_load_lds_dwordx4 v[72:73], off
	s_add_u32 s99, s26, 0x6680
	v_add_u32_e32 v128, s99, v154
	s_add_u32 m0, s98, 0xc00
	v_lshl_add_u64 v[72:73], v[128:129], 1, s[88:89]
	global_load_lds_dwordx4 v[72:73], off
	s_add_u32 s99, s26, 0x80
	v_add_u32_e32 v128, s99, v155
	s_add_u32 m0, s98, 0x4000
	v_lshl_add_u64 v[72:73], v[128:129], 1, s[50:51]
	global_load_lds_dwordx4 v[72:73], off
	s_add_u32 s99, s26, 0x2280
	v_add_u32_e32 v128, s99, v156
	s_add_u32 m0, s98, 0x4400
	v_lshl_add_u64 v[72:73], v[128:129], 1, s[50:51]
	global_load_lds_dwordx4 v[72:73], off
	s_add_u32 s99, s26, 0x4480
	v_add_u32_e32 v128, s99, v155
	s_add_u32 m0, s98, 0x4800
	v_lshl_add_u64 v[72:73], v[128:129], 1, s[50:51]
	global_load_lds_dwordx4 v[72:73], off
	s_add_u32 s99, s26, 0x6680
	v_add_u32_e32 v128, s99, v156
	s_add_u32 m0, s98, 0x4c00
	v_lshl_add_u64 v[72:73], v[128:129], 1, s[50:51]
	global_load_lds_dwordx4 v[72:73], off
.LBB0_1441:
	v_mfma_f32_32x32x16_bf16 v[48:63], v[76:79], v[84:87], v[48:63]
	s_mov_b64 s[34:35], -1
	s_and_b64 vcc, exec, s[30:31]
	v_mfma_f32_32x32x16_bf16 v[32:47], v[76:79], v[92:95], v[32:47]
	v_mfma_f32_32x32x16_bf16 v[16:31], v[64:67], v[84:87], v[16:31]
	v_mfma_f32_32x32x16_bf16 v[0:15], v[64:67], v[92:95], v[0:15]
	ds_read_b128 v[64:67], v139 offset:0x8000
	v_mfma_f32_32x32x16_bf16 v[48:63], v[68:71], v[80:83], v[48:63]
	v_mfma_f32_32x32x16_bf16 v[32:47], v[68:71], v[100:103], v[32:47]
	ds_read_b128 v[68:71], v139 offset:0x9000
	ds_read_b128 v[76:79], v141 offset:0x8000
	v_mfma_f32_32x32x16_bf16 v[16:31], v[96:99], v[80:83], v[16:31]
	ds_read_b128 v[80:83], v141 offset:0x9000
	ds_read_b128 v[84:87], v140 offset:0x8000
	ds_read_b128 v[72:75], v140 offset:0x9000
	ds_read_b128 v[92:95], v142 offset:0x8000
	ds_read_b128 v[88:91], v142 offset:0x9000
	v_mfma_f32_32x32x16_bf16 v[0:15], v[96:99], v[100:103], v[0:15]
	s_cbranch_vccz .LBB0_1443
	s_waitcnt vmcnt(0)
	s_mov_b64 s[34:35], 0

.LBB0_1447:
	v_mfma_f32_32x32x16_bf16 v[48:63], v[64:67], v[76:79], v[48:63]
	s_mov_b64 s[34:35], -1
	s_and_b64 vcc, exec, s[28:29]
	ds_read_b128 v[116:119], v157 offset:0x8000
	ds_read_b128 v[104:107], v157 offset:0x9000
	ds_read_b128 v[120:123], v159 offset:0x8000
	ds_read_b128 v[124:127], v159 offset:0x9000
	ds_read_b128 v[108:111], v158 offset:0x8000
	v_mfma_f32_32x32x16_bf16 v[32:47], v[64:67], v[80:83], v[32:47]
	ds_read_b128 v[96:99], v158 offset:0x9000
	ds_read_b128 v[112:115], v160 offset:0x8000
	ds_read_b128 v[100:103], v160 offset:0x9000
	v_mfma_f32_32x32x16_bf16 v[16:31], v[68:71], v[76:79], v[16:31]
	v_mfma_f32_32x32x16_bf16 v[0:15], v[68:71], v[80:83], v[0:15]
	v_mfma_f32_32x32x16_bf16 v[48:63], v[84:87], v[92:95], v[48:63]
	v_mfma_f32_32x32x16_bf16 v[32:47], v[84:87], v[88:91], v[32:47]
	v_mfma_f32_32x32x16_bf16 v[16:31], v[72:75], v[92:95], v[16:31]
	v_mfma_f32_32x32x16_bf16 v[0:15], v[72:75], v[88:91], v[0:15]
	s_cbranch_vccz .LBB0_1449
	s_waitcnt lgkmcnt(0)
	s_mov_b64 s[34:35], 0
.LBB0_1449:
	s_andn2_b64 vcc, exec, s[34:35]
	s_cbranch_vccnz .LBB0_1428
	s_waitcnt vmcnt(0)
.LBB0_1454:
	s_waitcnt lgkmcnt(0)
	s_cmp_gt_u32 s33, 24
	s_barrier
	s_cbranch_scc1 .LBB0_1427
	v_readfirstlane_b32 s98, v149
	s_nop 0
	s_lshl_b32 s98, s98, 1
	s_add_u32 s99, s26, 0xc0
	v_add_u32_e32 v128, s99, v153
	s_add_u32 m0, s98, 0x8000
	v_lshl_add_u64 v[64:65], v[128:129], 1, s[88:89]
	global_load_lds_dwordx4 v[64:65], off
	s_add_u32 s99, s26, 0x22c0
	v_add_u32_e32 v128, s99, v154
	s_add_u32 m0, s98, 0x8400
	v_lshl_add_u64 v[64:65], v[128:129], 1, s[88:89]
	global_load_lds_dwordx4 v[64:65], off
	s_add_u32 s99, s26, 0x44c0
	v_add_u32_e32 v128, s99, v153
	s_add_u32 m0, s98, 0x8800
	v_lshl_add_u64 v[64:65], v[128:129], 1, s[88:89]
	global_load_lds_dwordx4 v[64:65], off
	s_add_u32 s99, s26, 0x66c0
	v_add_u32_e32 v128, s99, v154
	s_add_u32 m0, s98, 0x8c00
	v_lshl_add_u64 v[64:65], v[128:129], 1, s[88:89]
	global_load_lds_dwordx4 v[64:65], off
	s_add_u32 s99, s26, 0xc0
	v_add_u32_e32 v128, s99, v155
	s_add_u32 m0, s98, 0xc000
	v_lshl_add_u64 v[64:65], v[128:129], 1, s[50:51]
	global_load_lds_dwordx4 v[64:65], off
	s_add_u32 s99, s26, 0x22c0
	v_add_u32_e32 v128, s99, v156
	s_add_u32 m0, s98, 0xc400
	v_lshl_add_u64 v[64:65], v[128:129], 1, s[50:51]
	global_load_lds_dwordx4 v[64:65], off
	s_add_u32 s99, s26, 0x44c0
	v_add_u32_e32 v128, s99, v155
	s_add_u32 m0, s98, 0xc800
	v_lshl_add_u64 v[64:65], v[128:129], 1, s[50:51]
	global_load_lds_dwordx4 v[64:65], off
	s_add_u32 s99, s26, 0x66c0
	v_add_u32_e32 v128, s99, v156
	s_add_u32 m0, s98, 0xcc00
	v_lshl_add_u64 v[64:65], v[128:129], 1, s[50:51]
	global_load_lds_dwordx4 v[64:65], off
	s_branch .LBB0_1427
